# v24 + attention ping copy: first PV V-fragment transposed LDS reads hoisted above the P pack/permute block (right after the last QK MFMA)
# speedup vs baseline: 1.0235x; 1.0235x over previous
; __device__ __forceinline__ void finishSM(f32x16& p0, f32x16& p1, float alpha, float& l_reg, bf16x8& pa0, bf16x8& pa1, bf16x8& pa2, bf16x8& pa3) {
; #pragma unroll
;     for (int r = 0; r < 16; ++r) p1[r] = __builtin_amdgcn_exp2f(p1[r]);
;     float ps = 0;
; #pragma unroll
;     for (int r = 0; r < 16; ++r) ps += p0[r];
; #pragma unroll
;     for (int r = 0; r < 16; ++r) ps += p1[r];
;     { auto rr = __builtin_amdgcn_permlane32_swap(__float_as_uint(ps), __float_as_uint(ps), false, false); ps = __uint_as_float(rr[0]) + __uint_as_float(rr[1]); }
;     l_reg = l_reg * alpha + ps;
;     ...
;     PK4(p0, 0, pa0); PK4(p0, 8, pa1); PK4(p1, 0, pa2); PK4(p1, 8, pa3);
;     ...
; }
; __device__ __forceinline__ void qkt(f32x16& p0, f32x16& p1, const char* Ks, const bf16x8* qr, const char* qrl, int r32, int hi) {
;     p0 = f32x16{}; p1 = f32x16{};
; #pragma unroll
;     for (int d0 = 0; d0 < 12; ++d0) { const int cb = (d0 * 16 + hi * 8) * 2;
;         const bf16x8 b0 = *reinterpret_cast<const bf16x8*>(Ks + KSWZ(r32, cb));
;         const bf16x8 b1 = *reinterpret_cast<const bf16x8*>(Ks + KSWZ(32 + r32, cb));
;         const bf16x8 qq = d0 < QREG ? qr[d0 < QREG ? d0 : 0] : *reinterpret_cast<const bf16x8*>(qrl + (d0 - QREG) * 1024);
;         p0 = __builtin_amdgcn_mfma_f32_32x32x16_bf16(b0, qq, p0, 0, 0, 0);
;         p1 = __builtin_amdgcn_mfma_f32_32x32x16_bf16(b1, qq, p1, 0, 0, 0); }
.LBB0_1380:
	v_add_u32_e32 v220, s14, v183
	ds_read_b128 v[64:67], v220
	ds_read_b128 v[68:71], v220 offset:16384
	v_add_u32_e32 v221, s14, v185
	ds_read_b128 v[222:225], v221
	ds_read_b128 v[226:229], v221 offset:16384
	v_add_f32_e32 v140, 0, v136
	s_waitcnt lgkmcnt(3)
	v_mfma_f32_32x32x16_bf16 v[80:95], v[64:67], v[116:119], 0
	v_add_f32_e32 v140, v166, v140
	v_add_f32_e32 v140, v137, v140
	v_add_f32_e32 v140, v167, v140
	v_add_f32_e32 v140, v138, v140
	v_add_f32_e32 v140, v168, v140
	v_add_f32_e32 v140, v139, v140
	v_add_f32_e32 v140, v165, v140
	s_waitcnt lgkmcnt(2)
	v_mfma_f32_32x32x16_bf16 v[64:79], v[68:71], v[116:119], 0
	v_add_f32_e32 v140, v144, v140
	v_add_f32_e32 v140, v146, v140
	v_add_f32_e32 v140, v145, v140
	v_add_f32_e32 v140, v164, v140
	v_exp_f32_e32 v132, v132
	v_add_f32_e32 v140, v141, v140
	v_exp_f32_e32 v133, v133
	s_waitcnt lgkmcnt(1)
	v_mfma_f32_32x32x16_bf16 v[80:95], v[222:225], v[112:115], v[80:95]
	v_add_u32_e32 v222, s14, v187
	v_add_u32_e32 v223, s14, v189
	v_add_f32_e32 v140, v143, v140
	v_exp_f32_e32 v134, v134
	v_add_f32_e32 v140, v142, v140
	v_exp_f32_e32 v135, v135
	v_add_f32_e32 v140, v147, v140
	s_waitcnt lgkmcnt(0)
	v_mfma_f32_32x32x16_bf16 v[64:79], v[226:229], v[112:115], v[64:79]
	ds_read_b128 v[224:227], v222
	ds_read_b128 v[228:231], v222 offset:16384
	v_exp_f32_e32 v122, v122
	v_add_f32_e32 v140, v132, v140
	v_exp_f32_e32 v123, v123
	v_add_f32_e32 v140, v133, v140
	v_exp_f32_e32 v124, v124
	v_add_f32_e32 v140, v134, v140
	s_waitcnt lgkmcnt(1)
	v_mfma_f32_32x32x16_bf16 v[80:95], v[224:227], v[108:111], v[80:95]
	v_exp_f32_e32 v125, v125
	v_add_f32_e32 v140, v135, v140
	v_exp_f32_e32 v126, v126
	v_add_f32_e32 v140, v122, v140
	v_exp_f32_e32 v127, v127
	v_add_f32_e32 v140, v123, v140
	v_exp_f32_e32 v130, v130
	s_waitcnt lgkmcnt(0)
	v_mfma_f32_32x32x16_bf16 v[64:79], v[228:231], v[108:111], v[64:79]
	ds_read_b128 v[224:227], v223
	ds_read_b128 v[228:231], v223 offset:16384
	v_add_f32_e32 v140, v124, v140
	v_exp_f32_e32 v131, v131
	v_add_f32_e32 v140, v125, v140
	v_exp_f32_e32 v120, v120
	v_add_f32_e32 v140, v126, v140
	v_exp_f32_e32 v121, v121
	s_waitcnt lgkmcnt(1)
	v_mfma_f32_32x32x16_bf16 v[80:95], v[224:227], v[104:107], v[80:95]
	v_add_u32_e32 v224, s14, v191
	v_add_u32_e32 v225, s14, v193
	v_add_f32_e32 v140, v127, v140
	v_exp_f32_e32 v128, v128
	v_add_f32_e32 v140, v130, v140
	v_exp_f32_e32 v129, v129
	v_add_f32_e32 v140, v131, v140
	s_waitcnt lgkmcnt(0)
	v_mfma_f32_32x32x16_bf16 v[64:79], v[228:231], v[104:107], v[64:79]
	ds_read_b128 v[226:229], v224
	ds_read_b128 v[230:233], v224 offset:16384
	v_add_f32_e32 v140, v120, v140
	v_add_f32_e32 v140, v121, v140
	v_add_f32_e32 v140, v128, v140
	s_waitcnt lgkmcnt(1)
	v_mfma_f32_32x32x16_bf16 v[80:95], v[226:229], v[100:103], v[80:95]
	s_waitcnt lgkmcnt(0)
	v_mfma_f32_32x32x16_bf16 v[64:79], v[230:233], v[100:103], v[64:79]
	ds_read_b128 v[226:229], v225
	ds_read_b128 v[230:233], v225 offset:16384
	s_waitcnt lgkmcnt(1)
	v_mfma_f32_32x32x16_bf16 v[80:95], v[226:229], v[96:99], v[80:95]
	v_add_u32_e32 v226, s14, v195
	v_add_u32_e32 v227, s14, v197
	s_waitcnt lgkmcnt(0)
	v_mfma_f32_32x32x16_bf16 v[64:79], v[230:233], v[96:99], v[64:79]
	ds_read_b128 v[228:231], v226
	ds_read_b128 v[232:235], v226 offset:16384
	ds_read_b128 v[236:239], v177
	s_waitcnt lgkmcnt(0)
	v_mfma_f32_32x32x16_bf16 v[80:95], v[228:231], v[236:239], v[80:95]
	v_mfma_f32_32x32x16_bf16 v[64:79], v[232:235], v[236:239], v[64:79]
	ds_read_b128 v[228:231], v227
	ds_read_b128 v[232:235], v227 offset:16384
	ds_read_b128 v[236:239], v177 offset:1024
	s_waitcnt lgkmcnt(0)
	v_mfma_f32_32x32x16_bf16 v[80:95], v[228:231], v[236:239], v[80:95]
	v_add_u32_e32 v229, s14, v199
	v_add_u32_e32 v228, s14, v201
	v_mfma_f32_32x32x16_bf16 v[64:79], v[232:235], v[236:239], v[64:79]
	ds_read_b128 v[230:233], v229
	ds_read_b128 v[234:237], v229 offset:16384
	ds_read_b128 v[238:241], v177 offset:2048
	s_waitcnt lgkmcnt(0)
	v_mfma_f32_32x32x16_bf16 v[80:95], v[230:233], v[238:241], v[80:95]
	v_mfma_f32_32x32x16_bf16 v[64:79], v[234:237], v[238:241], v[64:79]
	ds_read_b128 v[230:233], v228
	ds_read_b128 v[234:237], v228 offset:16384
	ds_read_b128 v[238:241], v177 offset:3072
	s_waitcnt lgkmcnt(0)
	v_mfma_f32_32x32x16_bf16 v[80:95], v[230:233], v[238:241], v[80:95]
	v_add_u32_e32 v230, s14, v203
	v_add_u32_e32 v231, s14, v205
	v_mfma_f32_32x32x16_bf16 v[64:79], v[234:237], v[238:241], v[64:79]
	ds_read_b128 v[232:235], v230
	ds_read_b128 v[236:239], v230 offset:16384
	ds_read_b128 v[240:243], v177 offset:4096
	s_waitcnt lgkmcnt(0)
	v_mfma_f32_32x32x16_bf16 v[80:95], v[232:235], v[240:243], v[80:95]
	v_mfma_f32_32x32x16_bf16 v[64:79], v[236:239], v[240:243], v[64:79]
	ds_read_b128 v[232:235], v231
	ds_read_b128 v[236:239], v231 offset:16384
	ds_read_b128 v[240:243], v177 offset:5120
	v_cvt_pk_bf16_f32 v136, v136, v166
	v_cvt_pk_bf16_f32 v137, v137, v167
	v_cvt_pk_bf16_f32 v138, v138, v168
	v_cvt_pk_bf16_f32 v139, v139, v165
	v_cvt_pk_bf16_f32 v144, v144, v146
	v_cvt_pk_bf16_f32 v145, v145, v164
	s_waitcnt lgkmcnt(0)
; __device__ __forceinline__ void finishSM(f32x16& p0, f32x16& p1, float alpha, float& l_reg, bf16x8& pa0, bf16x8& pa1, bf16x8& pa2, bf16x8& pa3) {
; #pragma unroll
;     for (int r = 0; r < 16; ++r) p1[r] = __builtin_amdgcn_exp2f(p1[r]);
;     float ps = 0;
; #pragma unroll
;     for (int r = 0; r < 16; ++r) ps += p0[r];
; #pragma unroll
;     for (int r = 0; r < 16; ++r) ps += p1[r];
;     { auto rr = __builtin_amdgcn_permlane32_swap(__float_as_uint(ps), __float_as_uint(ps), false, false); ps = __uint_as_float(rr[0]) + __uint_as_float(rr[1]); }
;     l_reg = l_reg * alpha + ps;
;     ...
;     PK4(p0, 0, pa0); PK4(p0, 8, pa1); PK4(p1, 0, pa2); PK4(p1, 8, pa3);
;     ...
; }
; __device__ __forceinline__ void qkt(f32x16& p0, f32x16& p1, const char* Ks, const bf16x8* qr, const char* qrl, int r32, int hi) {
;     p0 = f32x16{}; p1 = f32x16{};
; #pragma unroll
;     for (int d0 = 0; d0 < 12; ++d0) { const int cb = (d0 * 16 + hi * 8) * 2;
;         const bf16x8 b0 = *reinterpret_cast<const bf16x8*>(Ks + KSWZ(r32, cb));
;         const bf16x8 b1 = *reinterpret_cast<const bf16x8*>(Ks + KSWZ(32 + r32, cb));
;         const bf16x8 qq = d0 < QREG ? qr[d0 < QREG ? d0 : 0] : *reinterpret_cast<const bf16x8*>(qrl + (d0 - QREG) * 1024);
;         p0 = __builtin_amdgcn_mfma_f32_32x32x16_bf16(b0, qq, p0, 0, 0, 0);
;         p1 = __builtin_amdgcn_mfma_f32_32x32x16_bf16(b1, qq, p1, 0, 0, 0); }
; }
; __device__ __forceinline__ int v_st(int k, int c) { const int kk = (k & ~0xC) | ((k & 4) << 1) | ((k & 8) >> 1); return ((kk >> 3) * 4 + (c >> 5)) * 512 + ((kk & 7) * 32 + (c & 31)) * 2; }
; __device__ __forceinline__ int v_rd_base(int lane) { return ((lane & 3) << 3) | (((lane >> 2) & 3) << 6) | (((lane >> 4) & 1) << 5) | (((lane >> 5) & 1) << 8); }
; template <int OFF> __device__ __forceinline__ s16x4 tr_read(int vb) { s16x4 r; asm volatile("ds_read_b64_tr_b16 %0, %1 offset:%2" : "=&v"(r) : "v"(vb), "i"(OFF) : "memory"); return r; }
; template <int D0> __device__ __forceinline__ void pv_one(f32x16& od, int vb, bf16x8 pa0, bf16x8 pa1, bf16x8 pa2, bf16x8 pa3) {
;     const s16x4 l0 = tr_read<v_rd_off(D0, 0, 0)>(vb), h0 = tr_read<v_rd_off(D0, 0, 1)>(vb), l1 = tr_read<v_rd_off(D0, 1, 0)>(vb), h1 = tr_read<v_rd_off(D0, 1, 1)>(vb);
;     const s16x4 l2 = tr_read<v_rd_off(D0, 2, 0)>(vb), h2 = tr_read<v_rd_off(D0, 2, 1)>(vb), l3 = tr_read<v_rd_off(D0, 3, 0)>(vb), h3 = tr_read<v_rd_off(D0, 3, 1)>(vb);
	v_mfma_f32_32x32x16_bf16 v[80:95], v[232:235], v[240:243], v[80:95]
	v_add_f32_e32 v232, v129, v140
	v_mov_b32_e32 v233, v232
	v_cvt_pk_bf16_f32 v146, v141, v143
	v_cvt_pk_bf16_f32 v147, v142, v147
	v_cvt_pk_bf16_f32 v234, v132, v133
	v_cvt_pk_bf16_f32 v235, v134, v135
	s_nop 1
	v_permlane32_swap_b32_e32 v232, v233
	v_mfma_f32_32x32x16_bf16 v[64:79], v[236:239], v[240:243], v[64:79]
	ds_read_b64_tr_b16 v[242:243], v176 offset:0
	ds_read_b64_tr_b16 v[244:245], v176 offset:0x800
	ds_read_b64_tr_b16 v[246:247], v176 offset:0x1000
	ds_read_b64_tr_b16 v[248:249], v176 offset:0x1800
	ds_read_b64_tr_b16 v[250:251], v176 offset:0x2000
	ds_read_b64_tr_b16 v[252:253], v176 offset:0x2800
	ds_read_b64_tr_b16 v[208:209], v176 offset:0x3000
	ds_read_b64_tr_b16 v[210:211], v176 offset:0x3800
	v_cvt_pk_bf16_f32 v236, v122, v123
	v_permlane32_swap_b32_e32 v136, v138
	v_cvt_pk_bf16_f32 v237, v124, v125
	v_permlane32_swap_b32_e32 v234, v236
	v_cvt_pk_bf16_f32 v238, v126, v127
	v_cvt_pk_bf16_f32 v239, v130, v131
	v_cvt_pk_bf16_f32 v240, v120, v121
	v_cvt_pk_bf16_f32 v241, v128, v129
	v_permlane32_swap_b32_e32 v137, v139
	v_permlane32_swap_b32_e32 v144, v146
	v_permlane32_swap_b32_e32 v145, v147
	v_permlane32_swap_b32_e32 v235, v237
	v_permlane32_swap_b32_e32 v238, v240
	v_permlane32_swap_b32_e32 v239, v241
	v_lshl_add_u64 v[164:165], s[68:69], 0, v[156:157]
	s_mov_b32 s4, 0x23480000
	v_add_co_u32_e32 v120, vcc, s4, v164
	s_mov_b32 s4, 0x234a0000
	s_nop 0
	v_addc_co_u32_e32 v121, vcc, 0, v165, vcc
	v_add_co_u32_e32 v124, vcc, s4, v164
	v_lshl_add_u64 v[166:167], s[68:69], 0, v[154:155]
	s_nop 0
	v_addc_co_u32_e32 v125, vcc, 0, v165, vcc
	v_add_co_u32_e32 v128, vcc, s97, v166
	v_lshl_add_u64 v[168:169], s[68:69], 0, v[152:153]
	s_nop 0
	v_addc_co_u32_e32 v129, vcc, 0, v167, vcc
	v_add_co_u32_e32 v132, vcc, s97, v168
	v_lshl_add_u64 v[170:171], s[68:69], 0, v[150:151]
	s_nop 0
	v_addc_co_u32_e32 v133, vcc, 0, v169, vcc
	v_add_co_u32_e32 v140, vcc, s97, v170
	global_load_dwordx4 v[120:123], v[120:121], off
	s_nop 0
	global_load_dwordx4 v[124:127], v[124:125], off
	s_nop 0
	global_load_dwordx4 v[128:131], v[128:129], off
	s_nop 0
	global_load_dwordx4 v[132:135], v[132:133], off
	v_addc_co_u32_e32 v141, vcc, 0, v171, vcc
	global_load_dwordx4 v[140:143], v[140:141], off
	s_waitcnt lgkmcnt(0)
	s_nop 0
	v_mfma_f32_32x32x16_bf16 v[0:15], v[136:139], v[242:245], v[0:15]
	v_mfma_f32_32x32x16_bf16 v[0:15], v[144:147], v[246:249], v[0:15]
	v_mfma_f32_32x32x16_bf16 v[0:15], v[234:237], v[250:253], v[0:15]
	v_mfma_f32_32x32x16_bf16 v[0:15], v[238:241], v[208:211], v[0:15]
	ds_read_b64_tr_b16 v[208:209], v176 offset:0x200
	ds_read_b64_tr_b16 v[210:211], v176 offset:0xa00
	ds_read_b64_tr_b16 v[242:243], v176 offset:0x1200
	ds_read_b64_tr_b16 v[244:245], v176 offset:0x1a00
	ds_read_b64_tr_b16 v[246:247], v176 offset:0x2200
	ds_read_b64_tr_b16 v[248:249], v176 offset:0x2a00
	ds_read_b64_tr_b16 v[250:251], v176 offset:0x3200
	ds_read_b64_tr_b16 v[252:253], v176 offset:0x3a00
	s_waitcnt lgkmcnt(0)
	s_nop 0
	v_mfma_f32_32x32x16_bf16 v[48:63], v[136:139], v[208:211], v[48:63]
	ds_read_b64_tr_b16 v[208:209], v176 offset:0x400
	ds_read_b64_tr_b16 v[210:211], v176 offset:0xc00
	v_mfma_f32_32x32x16_bf16 v[48:63], v[144:147], v[242:245], v[48:63]
	ds_read_b64_tr_b16 v[242:243], v176 offset:0x1400
	ds_read_b64_tr_b16 v[244:245], v176 offset:0x1c00
	v_mfma_f32_32x32x16_bf16 v[48:63], v[234:237], v[246:249], v[48:63]
	ds_read_b64_tr_b16 v[246:247], v176 offset:0x2400
	ds_read_b64_tr_b16 v[248:249], v176 offset:0x2c00
	v_mfma_f32_32x32x16_bf16 v[48:63], v[238:241], v[250:253], v[48:63]
	ds_read_b64_tr_b16 v[250:251], v176 offset:0x3400
	ds_read_b64_tr_b16 v[252:253], v176 offset:0x3c00
	s_waitcnt lgkmcnt(0)
	v_mfma_f32_32x32x16_bf16 v[32:47], v[136:139], v[208:211], v[32:47]
	ds_read_b64_tr_b16 v[208:209], v176 offset:0x600
	ds_read_b64_tr_b16 v[210:211], v176 offset:0xe00
	v_mfma_f32_32x32x16_bf16 v[32:47], v[144:147], v[242:245], v[32:47]
	ds_read_b64_tr_b16 v[242:243], v176 offset:0x1600
	ds_read_b64_tr_b16 v[244:245], v176 offset:0x1e00
	v_mfma_f32_32x32x16_bf16 v[32:47], v[234:237], v[246:249], v[32:47]
	ds_read_b64_tr_b16 v[246:247], v176 offset:0x2600
	ds_read_b64_tr_b16 v[248:249], v176 offset:0x2e00
	v_mfma_f32_32x32x16_bf16 v[32:47], v[238:241], v[250:253], v[32:47]
	ds_read_b64_tr_b16 v[250:251], v176 offset:0x3600
	ds_read_b64_tr_b16 v[252:253], v176 offset:0x3e00
	s_waitcnt lgkmcnt(0)
	v_mfma_f32_32x32x16_bf16 v[16:31], v[136:139], v[208:211], v[16:31]
	v_max_f32_e32 v136, v81, v81
	v_max_f32_e32 v137, v80, v80
	v_max_f32_e32 v136, v137, v136
	v_max3_f32 v136, v136, v82, v83
	v_max3_f32 v136, v136, v84, v85
	v_max3_f32 v136, v136, v86, v87
	v_max3_f32 v136, v136, v88, v89
	v_max3_f32 v136, v136, v90, v91
	v_mfma_f32_32x32x16_bf16 v[16:31], v[144:147], v[242:245], v[16:31]
	v_max3_f32 v136, v136, v92, v93
	v_max3_f32 v136, v136, v94, v95
	v_max3_f32 v136, v136, v64, v65
	v_max3_f32 v136, v136, v66, v67
	v_max3_f32 v136, v136, v68, v69
	v_max3_f32 v136, v136, v70, v71
	v_max3_f32 v136, v136, v72, v73
	v_max3_f32 v136, v136, v74, v75
	v_mfma_f32_32x32x16_bf16 v[16:31], v[234:237], v[246:249], v[16:31]
	v_max3_f32 v136, v136, v76, v77
	v_max3_f32 v136, v136, v78, v79
	v_mov_b32_e32 v137, v136
	s_nop 1
	v_permlane32_swap_b32_e32 v136, v137
	v_max_f32_e32 v137, v137, v137
	v_max_f32_e32 v136, v136, v136
	v_max_f32_e32 v136, v136, v137
	v_sub_f32_e32 v137, v136, v158
	v_cmp_ge_f32_e32 vcc, s62, v137
	v_max_f32_e32 v137, v158, v158
	v_mfma_f32_32x32x16_bf16 v[16:31], v[238:241], v[250:253], v[16:31]
	v_max_f32_e32 v136, v137, v136
	v_sub_f32_e32 v137, v158, v136
	v_exp_f32_e32 v137, v137
	s_cmp_eq_u64 vcc, exec
	s_cselect_b64 s[4:5], -1, 0
	s_barrier
; #define SWRITE(b) do { *(bf16x8*)(V_lds + (b) * SHM_V + vst0) = vs0; *(bf16x8*)(V_lds + (b) * SHM_V + vst1) = vs1; \
;     *(bf16x8*)(K_lds + (b) * SHM_K + KSWZ(kr0, kc0 * 16)) = ks0; *(bf16x8*)(K_lds + (b) * SHM_K + KSWZ(kr1, kc1 * 16)) = ks1; *(bf16x8*)(K_lds + (b) * SHM_K + KSWZ(kr2, kc2 * 16)) = ks2; } while (0)
; #define SWAIT() asm volatile("s_waitcnt vmcnt(0)" ::: "memory")
; #define RESC(a) do { if (__any((a) < 1.f)) { if (hi == 0) al_l[r32] = (a); asm volatile("s_waitcnt lgkmcnt(0)" ::: "memory"); \
;     _Pragma("unroll") for (int d = 0; d < 4; ++d) _Pragma("unroll") for (int r = 0; r < 16; ++r) o[d][r] *= al_l[crow(r, hi)]; } } while (0)
; __device__ __forceinline__ void attn_unit(const bf16_t* __restrict__ Qb, const bf16_t* __restrict__ Kh, const bf16_t* __restrict__ Vh, bf16_t* __restrict__ Ob, int seq, char* lds) {
;     ...
;         __syncthreads(); SWAIT(); SWRITE(1);
;         RESC(alA); __syncthreads();
	s_waitcnt vmcnt(0)
	v_cndmask_b32_e64 v234, v137, 1.0, s[4:5]
	v_cmp_gt_f32_e32 vcc, 1.0, v234
	s_waitcnt vmcnt(4)
	ds_write_b128 v178, v[120:123]
	s_waitcnt vmcnt(3)
	ds_write_b128 v179, v[124:127]
	s_waitcnt vmcnt(2)
	ds_write_b128 v180, v[128:131] offset:32768
	s_waitcnt vmcnt(1)
	ds_write_b128 v181, v[132:135] offset:32768
	s_waitcnt vmcnt(0)
	ds_write_b128 v182, v[140:143] offset:32768
	s_cbranch_vccz .LBB0_1384
	s_and_saveexec_b64 s[12:13], s[2:3]
	ds_write_b32 v173, v234 offset:128
	s_or_b64 exec, exec, s[12:13]
	s_waitcnt lgkmcnt(0)
	v_add_u32_e32 v132, v149, v160
	ds_read_b128 v[120:123], v132 offset:224
	ds_read_b128 v[124:127], v132 offset:192
	ds_read_b128 v[128:131], v132 offset:160
	ds_read_b128 v[132:135], v132 offset:128
	s_waitcnt lgkmcnt(3)
	v_pk_mul_f32 v[12:13], v[12:13], v[120:121]
	s_waitcnt lgkmcnt(2)
	v_pk_mul_f32 v[8:9], v[8:9], v[124:125]
	s_waitcnt lgkmcnt(1)
	v_pk_mul_f32 v[4:5], v[4:5], v[128:129]
	v_pk_mul_f32 v[14:15], v[14:15], v[122:123]
	v_pk_mul_f32 v[10:11], v[10:11], v[126:127]
	v_pk_mul_f32 v[6:7], v[6:7], v[130:131]
	s_waitcnt lgkmcnt(0)
	v_pk_mul_f32 v[2:3], v[2:3], v[134:135]
	v_pk_mul_f32 v[0:1], v[0:1], v[132:133]
	v_pk_mul_f32 v[60:61], v[60:61], v[120:121]
	v_pk_mul_f32 v[56:57], v[56:57], v[124:125]
	v_pk_mul_f32 v[52:53], v[52:53], v[128:129]
	v_pk_mul_f32 v[62:63], v[62:63], v[122:123]
	v_pk_mul_f32 v[58:59], v[58:59], v[126:127]
	v_pk_mul_f32 v[54:55], v[54:55], v[130:131]
	v_pk_mul_f32 v[50:51], v[50:51], v[134:135]
	v_pk_mul_f32 v[48:49], v[48:49], v[132:133]
	v_pk_mul_f32 v[44:45], v[44:45], v[120:121]
	v_pk_mul_f32 v[40:41], v[40:41], v[124:125]
	v_pk_mul_f32 v[36:37], v[36:37], v[128:129]
	v_pk_mul_f32 v[46:47], v[46:47], v[122:123]
	v_pk_mul_f32 v[42:43], v[42:43], v[126:127]
	v_pk_mul_f32 v[38:39], v[38:39], v[130:131]
	v_pk_mul_f32 v[34:35], v[34:35], v[134:135]
	v_pk_mul_f32 v[32:33], v[32:33], v[132:133]
	v_pk_mul_f32 v[28:29], v[28:29], v[120:121]
	v_pk_mul_f32 v[24:25], v[24:25], v[124:125]
	v_pk_mul_f32 v[20:21], v[20:21], v[128:129]
	v_pk_mul_f32 v[30:31], v[30:31], v[122:123]
	v_pk_mul_f32 v[26:27], v[26:27], v[126:127]
	v_pk_mul_f32 v[22:23], v[22:23], v[130:131]
	v_pk_mul_f32 v[18:19], v[18:19], v[134:135]
	v_pk_mul_f32 v[16:17], v[16:17], v[132:133]
